# MLA L0 loop: triple-buffered K/V tiles, LDS-DMA two tiles ahead, scalar address block + DMA issue inside the first score chain, step-end scalar updates inside PV (L1 loop unchanged from v29)
# speedup vs baseline: 1.0021x; 1.0021x over previous
.LBB0_891:
	s_lshr_b32 s16, s19, 6
	s_and_b64 s[12:13], s[12:13], exec
	s_cselect_b32 s12, s19, s16
	s_and_b32 s17, s12, 7
	s_mul_i32 s12, s9, 0xc00
	s_mul_hi_u32 s13, s8, 0xc00
	s_add_i32 s13, s13, s12
	s_mul_i32 s12, s8, 0xc00
	v_readlane_b32 s20, v242, 21
	v_readlane_b32 s21, v242, 22
	s_add_u32 s12, s20, s12
	s_addc_u32 s13, s21, s13
	s_mul_i32 s16, s17, 0x180
	s_add_u32 s28, s12, s16
	s_addc_u32 s29, s13, 0
	s_mul_i32 s12, s1, 0xc00
	s_mul_hi_u32 s13, s0, 0xc00
	s_add_i32 s13, s13, s12
	s_mul_i32 s12, s0, 0xc00
	s_add_u32 s12, s27, s12
	s_addc_u32 s13, s30, s13
	s_add_u32 s12, s12, s16
	s_mul_i32 s20, s15, 0x3000000
	s_mul_hi_u32 s21, s14, 0x3000000
	s_addc_u32 s13, s13, 0
	s_add_i32 s21, s21, s20
	s_mul_i32 s20, s14, 0x3000000
	s_add_u32 s20, s27, s20
	s_addc_u32 s21, s30, s21
	s_add_u32 s22, s20, s16
	s_addc_u32 s23, s21, 0
	s_lshl_b64 s[0:1], s[0:1], 12
	s_add_u32 s0, s31, s0
	s_addc_u32 s1, s34, s1
	s_lshl_b32 s16, s17, 9
	s_add_u32 s0, s0, s16
	s_addc_u32 s1, s1, 0
	s_add_u32 s24, s0, 0x100
	s_addc_u32 s25, s1, 0
	s_lshl_b64 s[14:15], s[14:15], 26
	s_add_u32 s14, s31, s14
	s_addc_u32 s15, s34, s15
	s_add_u32 s14, s14, s16
	s_addc_u32 s15, s15, 0
	s_add_u32 s33, s14, 0x100
	v_readfirstlane_b32 s68, v0
	s_addc_u32 s35, s15, 0
	s_lshr_b32 s20, s68, 6
	s_lshl_b32 s16, s20, 5
	v_or_b32_e32 v4, s16, v1
	v_mov_b64_e32 v[2:3], s[28:29]
	s_movk_i32 s14, 0xc00
	v_mad_u64_u32 v[2:3], s[14:15], v4, s14, v[2:3]
	s_andn2_b32 s68, s68, 63
	v_lshl_add_u64 v[2:3], v[2:3], 0, v[148:149]
	global_load_dwordx4 v[142:145], v[2:3], off
	global_load_dwordx4 v[138:141], v[2:3], off offset:32
	global_load_dwordx4 v[134:137], v[2:3], off offset:64
	global_load_dwordx4 v[130:133], v[2:3], off offset:96
	global_load_dwordx4 v[126:129], v[2:3], off offset:128
	global_load_dwordx4 v[122:125], v[2:3], off offset:160
	global_load_dwordx4 v[118:121], v[2:3], off offset:192
	global_load_dwordx4 v[114:117], v[2:3], off offset:224
	global_load_dwordx4 v[110:113], v[2:3], off offset:256
	global_load_dwordx4 v[106:109], v[2:3], off offset:288
	global_load_dwordx4 v[102:105], v[2:3], off offset:320
	global_load_dwordx4 v[98:101], v[2:3], off offset:352
	v_or_b32_e32 v2, s68, v166
	v_mul_hi_i32 v3, v2, s11
	v_lshrrev_b32_e32 v4, 31, v3
	v_ashrrev_i32_e32 v3, 2, v3
	v_add_u32_e32 v3, v3, v4
	v_mul_lo_u32 v4, v3, 24
	v_sub_u32_e32 v4, v2, v4
	v_mul_lo_u32 v5, v3, s18
	v_lshrrev_b32_e32 v3, 1, v3
	v_bitop3_b32 v3, v3, v4, 7 bitop3:0x6c
	v_lshl_add_u32 v160, v3, 3, v5
	v_add_u32_e32 v3, 0x200, v2
	v_mul_hi_i32 v4, v3, s11
	v_lshrrev_b32_e32 v5, 31, v4
	v_ashrrev_i32_e32 v4, 2, v4
	v_add_u32_e32 v4, v4, v5
	v_mul_lo_u32 v5, v4, 24
	v_sub_u32_e32 v3, v3, v5
	v_mul_lo_u32 v5, v4, s18
	v_lshrrev_b32_e32 v4, 1, v4
	v_bitop3_b32 v3, v4, v3, 7 bitop3:0x6c
	v_lshl_add_u32 v162, v3, 3, v5
	v_add_u32_e32 v3, 0x400, v2
	v_mul_hi_i32 v4, v3, s11
	v_lshrrev_b32_e32 v5, 31, v4
	v_ashrrev_i32_e32 v4, 2, v4
	v_add_u32_e32 v4, v4, v5
	s_ashr_i32 s14, s68, 4
	v_mul_lo_u32 v5, v4, 24
	s_and_b32 s15, s14, 0x1ffff0
	s_lshr_b32 s14, s14, 1
	v_sub_u32_e32 v3, v3, v5
	v_mul_lo_u32 v5, v4, s18
	v_lshrrev_b32_e32 v4, 1, v4
	s_and_b32 s14, s14, 4
	v_bitop3_b32 v3, v4, v3, 7 bitop3:0x6c
	s_or_b32 s14, s15, s14
	v_lshl_add_u32 v170, v3, 3, v5
	v_or_b32_e32 v3, s14, v169
	s_add_i32 s14, s68, 0x200
	s_ashr_i32 s14, s14, 4
	s_and_b32 s15, s14, 0x1ffff0
	s_lshr_b32 s14, s14, 1
	s_and_b32 s14, s14, 4
	v_and_or_b32 v2, v2, s10, v165
	s_or_b32 s14, s15, s14
	v_lshl_or_b32 v172, v3, 11, v2
	v_or_b32_e32 v3, s14, v169
	s_lshl_b32 s14, s20, 10
	s_add_i32 s69, s14, 0
	v_ashrrev_i32_e32 v161, 31, v160
	v_lshl_or_b32 v174, v3, 11, v2
	s_add_i32 m0, s69, 0x8000
	v_lshl_add_u64 v[2:3], v[160:161], 1, s[12:13]
	v_ashrrev_i32_e32 v163, 31, v162
	global_load_lds_dwordx4 v[2:3], off
	v_lshl_add_u64 v[2:3], v[162:163], 1, s[12:13]
	s_add_i32 m0, s69, 0xa000
	v_ashrrev_i32_e32 v171, 31, v170
	global_load_lds_dwordx4 v[2:3], off
	v_lshl_add_u64 v[2:3], v[170:171], 1, s[12:13]
	s_add_i32 m0, s69, 0xc000
	v_ashrrev_i32_e32 v173, 31, v172
	global_load_lds_dwordx4 v[2:3], off
	v_lshl_add_u64 v[2:3], v[172:173], 1, s[0:1]
	v_lshl_add_u64 v[2:3], v[2:3], 0, s[6:7]
	s_mov_b32 m0, s69
	v_ashrrev_i32_e32 v175, 31, v174
	global_load_lds_dwordx4 v[2:3], off
	v_lshl_add_u64 v[2:3], v[174:175], 1, s[0:1]
	v_lshl_add_u64 v[2:3], v[2:3], 0, s[6:7]
	s_add_i32 m0, s69, 0x2000
	v_mov_b32_e32 v151, 0
	global_load_lds_dwordx4 v[2:3], off
	s_waitcnt vmcnt(0)
	s_add_i32 s0, s4, 1
	s_mov_b32 s4, 0
	s_mov_b64 s[14:15], 0x80
	v_mov_b32_e32 v2, 0
	v_mov_b32_e32 v3, v151
	v_mov_b32_e32 v4, v151
	v_mov_b32_e32 v5, v151
	v_mov_b32_e32 v6, v151
	v_mov_b32_e32 v7, v151
	v_mov_b32_e32 v8, v151
	v_mov_b32_e32 v9, v151
	v_mov_b32_e32 v10, v151
	v_mov_b32_e32 v11, v151
	v_mov_b32_e32 v12, v151
	v_mov_b32_e32 v13, v151
	v_mov_b32_e32 v14, v151
	v_mov_b32_e32 v15, v151
	v_mov_b32_e32 v16, v151
	v_mov_b32_e32 v17, v151
	v_mov_b32_e32 v18, 0
	v_mov_b32_e32 v19, v151
	v_mov_b32_e32 v20, v151
	v_mov_b32_e32 v21, v151
	v_mov_b32_e32 v22, v151
	v_mov_b32_e32 v23, v151
	v_mov_b32_e32 v24, v151
	v_mov_b32_e32 v25, v151
	v_mov_b32_e32 v26, v151
	v_mov_b32_e32 v27, v151
	v_mov_b32_e32 v28, v151
	v_mov_b32_e32 v29, v151
	v_mov_b32_e32 v30, v151
	v_mov_b32_e32 v31, v151
	v_mov_b32_e32 v32, v151
	v_mov_b32_e32 v33, v151
	v_mov_b32_e32 v34, 0
	v_mov_b32_e32 v35, v151
	v_mov_b32_e32 v36, v151
	v_mov_b32_e32 v37, v151
	v_mov_b32_e32 v38, v151
	v_mov_b32_e32 v39, v151
	v_mov_b32_e32 v40, v151
	v_mov_b32_e32 v41, v151
	v_mov_b32_e32 v42, v151
	v_mov_b32_e32 v43, v151
	v_mov_b32_e32 v44, v151
	v_mov_b32_e32 v45, v151
	v_mov_b32_e32 v46, v151
	v_mov_b32_e32 v47, v151
	v_mov_b32_e32 v48, v151
	v_mov_b32_e32 v49, v151
	v_mov_b32_e32 v50, 0
	v_mov_b32_e32 v51, v151
	v_mov_b32_e32 v52, v151
	v_mov_b32_e32 v53, v151
	v_mov_b32_e32 v54, v151
	v_mov_b32_e32 v55, v151
	v_mov_b32_e32 v56, v151
	v_mov_b32_e32 v57, v151
	v_mov_b32_e32 v58, v151
	v_mov_b32_e32 v59, v151
	v_mov_b32_e32 v60, v151
	v_mov_b32_e32 v61, v151
	v_mov_b32_e32 v62, v151
	v_mov_b32_e32 v63, v151
	v_mov_b32_e32 v64, v151
	v_mov_b32_e32 v65, v151
	s_waitcnt vmcnt(0) lgkmcnt(0)
	s_barrier
	s_mov_b32 s98, 0
	s_mov_b32 s99, 0x4000
	s_mov_b32 s101, 0x1a000
	s_mov_b32 s100, 0
	s_add_u32 s38, s12, 0x30000
	s_addc_u32 s39, s13, 0
	s_add_u32 s28, s24, 0x40000
	s_addc_u32 s29, s25, 0
	s_add_i32 s36, s69, 0x6000
	s_add_i32 s21, s69, 0x4000
	s_add_i32 m0, s36, 0x8000
	v_lshl_add_u64 v[66:67], v[160:161], 1, s[38:39]
	global_load_lds_dwordx4 v[66:67], off
	s_add_i32 m0, s36, 0xa000
	v_lshl_add_u64 v[68:69], v[162:163], 1, s[38:39]
	global_load_lds_dwordx4 v[68:69], off
	s_add_i32 m0, s36, 0xc000
	v_lshl_add_u64 v[66:67], v[170:171], 1, s[38:39]
	global_load_lds_dwordx4 v[66:67], off
	s_mov_b32 m0, s21
	v_lshl_add_u64 v[68:69], v[172:173], 1, s[28:29]
	global_load_lds_dwordx4 v[68:69], off
	s_add_i32 m0, s21, 0x2000
	v_lshl_add_u64 v[66:67], v[174:175], 1, s[28:29]
	global_load_lds_dwordx4 v[66:67], off
.LBB0_892:
	s_mul_i32 s21, s100, 0x6000
	v_add_u32_e32 v70, s21, v179
	v_add_u32_e32 v71, v70, v178
	v_add_u32_e32 v153, v70, v180
	v_add_u32_e32 v155, v70, v181
	ds_read_b128 v[194:197], v71 offset:32768
	ds_read_b128 v[244:247], v153 offset:32768
	ds_read_b128 v[248:251], v155 offset:32768
	v_add_u32_e32 v157, v70, v182
	v_add_u32_e32 v159, v70, v183
	v_add_u32_e32 v193, v70, v184
	v_add_u32_e32 v198, v70, v185
	v_add_u32_e32 v199, v70, v186
	v_add_u32_e32 v200, v70, v187
	v_add_u32_e32 v201, v70, v188
	v_add_u32_e32 v202, v70, v189
	v_add_u32_e32 v203, v70, v190
	ds_read_b128 v[252:255], v157 offset:32768
	v_sub_co_u32_e64 v66, s[28:29], s4, 2
	s_add_i32 s1, s4, 1
	s_nop 0
	v_readfirstlane_b32 s4, v66
	s_waitcnt lgkmcnt(3)
	v_mfma_f32_32x32x16_bf16 v[82:97], v[194:197], v[142:145], 0
	ds_read_b128 v[194:197], v159 offset:32768
	s_lshl_b64 s[36:37], s[4:5], 6
	s_and_b64 s[38:39], s[28:29], exec
	s_cselect_b32 s37, s15, s37
	s_cselect_b32 s36, s14, s36
	s_mul_i32 s39, s37, 0xc00
	s_mul_hi_u32 s40, s36, 0xc00
	s_waitcnt lgkmcnt(3)
	v_mfma_f32_32x32x16_bf16 v[82:97], v[244:247], v[138:141], v[82:97]
	ds_read_b128 v[244:247], v193 offset:32768
	s_cselect_b32 s4, s13, s23
	s_cselect_b32 s38, s12, s22
	s_add_i32 s40, s40, s39
	s_mul_i32 s39, s36, 0xc00
	s_add_u32 s38, s38, s39
	s_addc_u32 s39, s4, s40
	s_waitcnt lgkmcnt(3)
	v_mfma_f32_32x32x16_bf16 v[82:97], v[248:251], v[134:137], v[82:97]
	ds_read_b128 v[248:251], v198 offset:32768
	s_add_i32 s4, s100, 2
	s_add_i32 s21, s100, -1
	s_cmp_lt_u32 s4, 3
	s_cselect_b32 s4, s4, s21
	s_mulk_i32 s4, 0x6000
	s_add_i32 s4, s69, s4
	s_waitcnt lgkmcnt(3)
	v_mfma_f32_32x32x16_bf16 v[82:97], v[252:255], v[130:133], v[82:97]
	ds_read_b128 v[252:255], v199 offset:32768
	s_add_i32 m0, s4, 0x8000
	v_lshl_add_u64 v[66:67], v[160:161], 1, s[38:39]
	global_load_lds_dwordx4 v[66:67], off
	s_waitcnt lgkmcnt(3)
	v_mfma_f32_32x32x16_bf16 v[82:97], v[194:197], v[126:129], v[82:97]
	ds_read_b128 v[194:197], v200 offset:32768
	s_add_i32 m0, s4, 0xa000
	v_lshl_add_u64 v[66:67], v[162:163], 1, s[38:39]
	global_load_lds_dwordx4 v[66:67], off
	s_waitcnt lgkmcnt(3)
	v_mfma_f32_32x32x16_bf16 v[82:97], v[244:247], v[122:125], v[82:97]
	ds_read_b128 v[244:247], v201 offset:32768
	s_add_i32 m0, s4, 0xc000
	v_lshl_add_u64 v[66:67], v[170:171], 1, s[38:39]
	global_load_lds_dwordx4 v[66:67], off
	s_waitcnt lgkmcnt(3)
	v_mfma_f32_32x32x16_bf16 v[82:97], v[248:251], v[118:121], v[82:97]
	ds_read_b128 v[248:251], v202 offset:32768
	s_lshl_b64 s[36:37], s[36:37], 12
	s_and_b64 s[28:29], s[28:29], exec
	s_cselect_b32 s28, s24, s33
	s_cselect_b32 s21, s25, s35
	s_add_u32 s28, s28, s36
	s_addc_u32 s29, s21, s37
	s_waitcnt lgkmcnt(3)
	v_mfma_f32_32x32x16_bf16 v[82:97], v[252:255], v[114:117], v[82:97]
	ds_read_b128 v[252:255], v203 offset:32768
	s_add_i32 s36, s69, s101
	s_mov_b32 m0, s36
	v_lshl_add_u64 v[66:67], v[172:173], 1, s[28:29]
	global_load_lds_dwordx4 v[66:67], off
	s_waitcnt lgkmcnt(3)
	v_mfma_f32_32x32x16_bf16 v[82:97], v[194:197], v[110:113], v[82:97]
	ds_read_b128 v[194:197], v71 offset:45056
	s_add_i32 m0, s36, 0x2000
	v_lshl_add_u64 v[66:67], v[174:175], 1, s[28:29]
	global_load_lds_dwordx4 v[66:67], off
	s_waitcnt lgkmcnt(3)
	v_mfma_f32_32x32x16_bf16 v[82:97], v[244:247], v[106:109], v[82:97]
	ds_read_b128 v[244:247], v153 offset:45056
	s_mov_b32 s4, s98
	s_waitcnt lgkmcnt(3)
	v_mfma_f32_32x32x16_bf16 v[82:97], v[248:251], v[102:105], v[82:97]
	ds_read_b128 v[248:251], v155 offset:45056
	s_waitcnt lgkmcnt(3)
	v_mfma_f32_32x32x16_bf16 v[82:97], v[252:255], v[98:101], v[82:97]
	ds_read_b128 v[252:255], v157 offset:45056
	s_nop 10
	v_exp_f32_e32 v204, v88
	v_exp_f32_e32 v205, v89
	v_exp_f32_e32 v206, v90
	v_exp_f32_e32 v207, v91
	v_exp_f32_e32 v208, v92
	v_exp_f32_e32 v209, v93
	v_exp_f32_e32 v210, v94
	s_waitcnt lgkmcnt(3)
	v_mfma_f32_32x32x16_bf16 v[66:81], v[194:197], v[142:145], 0
	ds_read_b128 v[194:197], v159 offset:45056
	v_exp_f32_e32 v211, v95
	v_exp_f32_e32 v212, v96
	v_exp_f32_e32 v213, v97
	v_add_u32_e32 v153, s4, v176
	v_cvt_pk_bf16_f32 v88, v210, v211
	v_cvt_pk_bf16_f32 v89, v212, v213
	s_waitcnt lgkmcnt(3)
	v_mfma_f32_32x32x16_bf16 v[66:81], v[244:247], v[138:141], v[66:81]
	ds_read_b128 v[244:247], v193 offset:45056
	v_exp_f32_e32 v155, v82
	s_waitcnt lgkmcnt(3)
	v_mfma_f32_32x32x16_bf16 v[66:81], v[248:251], v[134:137], v[66:81]
	ds_read_b128 v[248:251], v198 offset:45056
	v_exp_f32_e32 v157, v83
	s_nop 0
	v_cvt_pk_bf16_f32 v82, v155, v157
	s_waitcnt lgkmcnt(3)
	v_mfma_f32_32x32x16_bf16 v[66:81], v[252:255], v[130:133], v[66:81]
	ds_read_b128 v[252:255], v199 offset:45056
	v_exp_f32_e32 v159, v84
	s_waitcnt lgkmcnt(3)
	v_mfma_f32_32x32x16_bf16 v[66:81], v[194:197], v[126:129], v[66:81]
	ds_read_b128 v[194:197], v200 offset:45056
	v_exp_f32_e32 v193, v85
	v_cvt_pk_bf16_f32 v85, v204, v205
	v_cvt_pk_bf16_f32 v83, v159, v193
	s_nop 1
	v_permlane32_swap_b32_e32 v83, v85
	s_waitcnt lgkmcnt(3)
	v_mfma_f32_32x32x16_bf16 v[66:81], v[244:247], v[122:125], v[66:81]
	ds_read_b128 v[244:247], v201 offset:45056
	s_waitcnt lgkmcnt(3)
	v_mfma_f32_32x32x16_bf16 v[66:81], v[248:251], v[118:121], v[66:81]
	ds_read_b128 v[248:251], v202 offset:45056
	s_waitcnt lgkmcnt(3)
	v_mfma_f32_32x32x16_bf16 v[66:81], v[252:255], v[114:117], v[66:81]
	ds_read_b128 v[252:255], v203 offset:45056
	s_waitcnt lgkmcnt(3)
	v_mfma_f32_32x32x16_bf16 v[66:81], v[194:197], v[110:113], v[66:81]
	s_waitcnt lgkmcnt(2)
	v_mfma_f32_32x32x16_bf16 v[66:81], v[244:247], v[106:109], v[66:81]
	v_exp_f32_e32 v202, v86
	v_cvt_pk_bf16_f32 v86, v206, v207
	s_nop 1
	v_permlane32_swap_b32_e32 v86, v88
	s_waitcnt lgkmcnt(1)
	v_mfma_f32_32x32x16_bf16 v[66:81], v[248:251], v[102:105], v[66:81]
	v_exp_f32_e32 v203, v87
	v_cvt_pk_bf16_f32 v87, v208, v209
	s_nop 1
	v_permlane32_swap_b32_e32 v87, v89
	v_cvt_pk_bf16_f32 v84, v202, v203
	s_nop 1
	v_permlane32_swap_b32_e32 v82, v84
	s_waitcnt lgkmcnt(0)
	v_mfma_f32_32x32x16_bf16 v[66:81], v[252:255], v[98:101], v[66:81]
	ds_read_b64_tr_b16 v[90:91], v153 offset:0
	ds_read_b64_tr_b16 v[92:93], v153 offset:0x800
	ds_read_b64_tr_b16 v[94:95], v153 offset:0x1000
	ds_read_b64_tr_b16 v[96:97], v153 offset:0x1800
	ds_read_b64_tr_b16 v[194:195], v153 offset:0x200
	ds_read_b64_tr_b16 v[196:197], v153 offset:0xa00
	ds_read_b64_tr_b16 v[198:199], v153 offset:0x1200
	ds_read_b64_tr_b16 v[200:201], v153 offset:0x1a00
	s_waitcnt lgkmcnt(4)
	s_nop 0
	v_mfma_f32_32x32x16_bf16 v[2:17], v[82:85], v[90:93], v[2:17]
	s_nop 9
	v_exp_f32_e32 v214, v66
	v_exp_f32_e32 v215, v67
	v_exp_f32_e32 v216, v68
	v_exp_f32_e32 v217, v69
	v_mfma_f32_32x32x16_bf16 v[2:17], v[86:89], v[94:97], v[2:17]
	ds_read_b64_tr_b16 v[66:67], v153 offset:0x400
	ds_read_b64_tr_b16 v[68:69], v153 offset:0xc00
	ds_read_b64_tr_b16 v[90:91], v153 offset:0x1400
	ds_read_b64_tr_b16 v[92:93], v153 offset:0x1c00
	s_waitcnt lgkmcnt(4)
	v_mfma_f32_32x32x16_bf16 v[18:33], v[82:85], v[194:197], v[18:33]
	v_exp_f32_e32 v194, v70
	v_exp_f32_e32 v195, v71
	v_exp_f32_e32 v196, v72
	v_exp_f32_e32 v197, v73
	v_mfma_f32_32x32x16_bf16 v[18:33], v[86:89], v[198:201], v[18:33]
	ds_read_b64_tr_b16 v[70:71], v153 offset:0x600
	ds_read_b64_tr_b16 v[72:73], v153 offset:0xe00
	ds_read_b64_tr_b16 v[94:95], v153 offset:0x1600
	ds_read_b64_tr_b16 v[96:97], v153 offset:0x1e00
	s_waitcnt lgkmcnt(4)
	v_mfma_f32_32x32x16_bf16 v[34:49], v[82:85], v[66:69], v[34:49]
	v_exp_f32_e32 v198, v74
	v_exp_f32_e32 v199, v75
	v_exp_f32_e32 v200, v76
	v_exp_f32_e32 v201, v77
	v_mfma_f32_32x32x16_bf16 v[34:49], v[86:89], v[90:93], v[34:49]
	ds_read_b64_tr_b16 v[66:67], v153 offset:0x2000
	ds_read_b64_tr_b16 v[68:69], v153 offset:0x2800
	ds_read_b64_tr_b16 v[74:75], v153 offset:0x3000
	ds_read_b64_tr_b16 v[76:77], v153 offset:0x3800
	s_waitcnt lgkmcnt(4)
	v_mfma_f32_32x32x16_bf16 v[50:65], v[82:85], v[70:73], v[50:65]
	v_exp_f32_e32 v249, v78
	v_exp_f32_e32 v250, v79
	v_cvt_pk_bf16_f32 v72, v194, v195
	v_cvt_pk_bf16_f32 v73, v196, v197
	v_mfma_f32_32x32x16_bf16 v[50:65], v[86:89], v[94:97], v[50:65]
	v_exp_f32_e32 v251, v80
	v_exp_f32_e32 v248, v81
	v_cvt_pk_bf16_f32 v78, v198, v199
	v_cvt_pk_bf16_f32 v79, v200, v201
	v_cvt_pk_bf16_f32 v80, v249, v250
	v_cvt_pk_bf16_f32 v70, v214, v215
	v_cvt_pk_bf16_f32 v71, v216, v217
	v_permlane32_swap_b32_e32 v78, v80
	v_cvt_pk_bf16_f32 v81, v251, v248
	v_permlane32_swap_b32_e32 v70, v72
	v_permlane32_swap_b32_e32 v71, v73
	s_nop 0
	v_permlane32_swap_b32_e32 v79, v81
	ds_read_b64_tr_b16 v[82:83], v153 offset:0x2200
	ds_read_b64_tr_b16 v[84:85], v153 offset:0x2a00
	ds_read_b64_tr_b16 v[86:87], v153 offset:0x3200
	ds_read_b64_tr_b16 v[88:89], v153 offset:0x3a00
	s_waitcnt lgkmcnt(4)
	s_nop 0
	v_mfma_f32_32x32x16_bf16 v[2:17], v[70:73], v[66:69], v[2:17]
	s_mov_b32 s36, s98
	s_mov_b32 s98, s99
	s_mov_b32 s99, s101
	v_add_f32_e32 v246, v155, v157
	v_add_f32_e32 v247, v214, v215
	v_add_f32_e32 v246, v246, v159
	v_add_f32_e32 v247, v247, v216
	v_mfma_f32_32x32x16_bf16 v[2:17], v[78:81], v[74:77], v[2:17]
	s_mov_b32 s101, s36
	s_add_i32 s100, s100, 1
	s_cmp_eq_u32 s100, 3
	v_add_f32_e32 v246, v246, v193
	v_add_f32_e32 v247, v247, v217
	v_add_f32_e32 v246, v246, v202
	v_add_f32_e32 v247, v247, v194
	ds_read_b64_tr_b16 v[66:67], v153 offset:0x2400
	ds_read_b64_tr_b16 v[68:69], v153 offset:0x2c00
	ds_read_b64_tr_b16 v[74:75], v153 offset:0x3400
	ds_read_b64_tr_b16 v[76:77], v153 offset:0x3c00
	s_waitcnt lgkmcnt(4)
	v_mfma_f32_32x32x16_bf16 v[18:33], v[70:73], v[82:85], v[18:33]
	s_cselect_b32 s100, 0, s100
	s_add_u32 s14, s14, 64
	s_addc_u32 s15, s15, 0
	v_add_f32_e32 v246, v246, v203
	v_add_f32_e32 v247, v247, v195
	v_add_f32_e32 v246, v246, v204
	v_add_f32_e32 v247, v247, v196
	v_mfma_f32_32x32x16_bf16 v[18:33], v[78:81], v[86:89], v[18:33]
	v_add_f32_e32 v246, v246, v205
	v_add_f32_e32 v247, v247, v197
	v_add_f32_e32 v246, v246, v206
	v_add_f32_e32 v247, v247, v198
	ds_read_b64_tr_b16 v[82:83], v153 offset:0x2600
	ds_read_b64_tr_b16 v[84:85], v153 offset:0x2e00
	ds_read_b64_tr_b16 v[86:87], v153 offset:0x3600
	ds_read_b64_tr_b16 v[88:89], v153 offset:0x3e00
	s_waitcnt lgkmcnt(4)
	v_mfma_f32_32x32x16_bf16 v[34:49], v[70:73], v[66:69], v[34:49]
	v_add_f32_e32 v246, v246, v207
	v_add_f32_e32 v247, v247, v199
	v_add_f32_e32 v246, v246, v208
	v_add_f32_e32 v247, v247, v200
	v_mfma_f32_32x32x16_bf16 v[34:49], v[78:81], v[74:77], v[34:49]
	v_add_f32_e32 v246, v246, v209
	v_add_f32_e32 v247, v247, v201
	v_add_f32_e32 v246, v246, v210
	v_add_f32_e32 v247, v247, v249
	s_waitcnt lgkmcnt(0)
	v_mfma_f32_32x32x16_bf16 v[50:65], v[70:73], v[82:85], v[50:65]
	v_add_f32_e32 v246, v246, v211
	v_add_f32_e32 v247, v247, v250
	v_add_f32_e32 v246, v246, v212
	v_add_f32_e32 v247, v247, v251
	v_add_f32_e32 v246, v246, v213
	v_add_f32_e32 v247, v247, v248
	v_add_f32_e32 v246, v246, v247
	v_mov_b32_e32 v247, v246
	s_nop 1
	v_permlane32_swap_b32_e32 v246, v247
	v_add_f32_e32 v246, v246, v247
	v_add_f32_e32 v151, v151, v246
	s_waitcnt vmcnt(5)
	s_cmp_eq_u32 s0, s1
	s_mov_b32 s4, s1
	s_waitcnt vmcnt(5)
	s_barrier
	v_mfma_f32_32x32x16_bf16 v[50:65], v[78:81], v[86:89], v[50:65]
	s_cbranch_scc0 .LBB0_892
	s_lshl_b32 s1, s68, 2
	s_add_i32 s4, s1, 0
	s_add_i32 s4, s4, 0x1e000
	s_mul_i32 s1, s100, 0x6000
	v_add_u32_e32 v70, s1, v179
	v_add_u32_e32 v71, v70, v178
	ds_read_b128 v[66:69], v71 offset:32768
	v_add_u32_e32 v153, v70, v180
	v_add_u32_e32 v155, v70, v181
	v_add_u32_e32 v157, v70, v182
	v_add_u32_e32 v159, v70, v183
	v_add_u32_e32 v160, v70, v184
	v_add_u32_e32 v161, v70, v185
	v_add_u32_e32 v162, v70, v186
	v_add_u32_e32 v163, v70, v187
	s_waitcnt lgkmcnt(0)
	v_mfma_f32_32x32x16_bf16 v[82:97], v[66:69], v[142:145], 0
	ds_read_b128 v[66:69], v153 offset:32768
	v_add_u32_e32 v170, v70, v188
	v_add_u32_e32 v171, v70, v189
	v_add_u32_e32 v172, v70, v190
	s_waitcnt lgkmcnt(0)
	v_mfma_f32_32x32x16_bf16 v[82:97], v[66:69], v[138:141], v[82:97]
	ds_read_b128 v[66:69], v155 offset:32768
	s_waitcnt lgkmcnt(0)
	v_mfma_f32_32x32x16_bf16 v[82:97], v[66:69], v[134:137], v[82:97]
	ds_read_b128 v[66:69], v157 offset:32768
	s_waitcnt lgkmcnt(0)
	v_mfma_f32_32x32x16_bf16 v[82:97], v[66:69], v[130:133], v[82:97]
	ds_read_b128 v[66:69], v159 offset:32768
	s_waitcnt lgkmcnt(0)
	v_mfma_f32_32x32x16_bf16 v[82:97], v[66:69], v[126:129], v[82:97]
	ds_read_b128 v[66:69], v160 offset:32768
	s_waitcnt lgkmcnt(0)
	v_mfma_f32_32x32x16_bf16 v[82:97], v[66:69], v[122:125], v[82:97]
	ds_read_b128 v[66:69], v161 offset:32768
	s_waitcnt lgkmcnt(0)
	v_mfma_f32_32x32x16_bf16 v[82:97], v[66:69], v[118:121], v[82:97]
	ds_read_b128 v[66:69], v162 offset:32768
	s_waitcnt lgkmcnt(0)
	v_mfma_f32_32x32x16_bf16 v[82:97], v[66:69], v[114:117], v[82:97]
	ds_read_b128 v[66:69], v163 offset:32768
	s_waitcnt lgkmcnt(0)
	v_mfma_f32_32x32x16_bf16 v[82:97], v[66:69], v[110:113], v[82:97]
	ds_read_b128 v[66:69], v170 offset:32768
	s_waitcnt lgkmcnt(0)
	v_mfma_f32_32x32x16_bf16 v[82:97], v[66:69], v[106:109], v[82:97]
	ds_read_b128 v[66:69], v171 offset:32768
	s_waitcnt lgkmcnt(0)
	v_mfma_f32_32x32x16_bf16 v[82:97], v[66:69], v[102:105], v[82:97]
	ds_read_b128 v[66:69], v172 offset:32768
	s_waitcnt lgkmcnt(0)
	v_mfma_f32_32x32x16_bf16 v[82:97], v[66:69], v[98:101], v[82:97]
	ds_read_b128 v[66:69], v71 offset:45056
	s_waitcnt lgkmcnt(0)
	v_mfma_f32_32x32x16_bf16 v[66:81], v[66:69], v[142:145], 0
	ds_read_b128 v[142:145], v153 offset:45056
	s_waitcnt lgkmcnt(0)
	v_mfma_f32_32x32x16_bf16 v[66:81], v[142:145], v[138:141], v[66:81]
	ds_read_b128 v[138:141], v155 offset:45056
	s_waitcnt lgkmcnt(0)
	v_mfma_f32_32x32x16_bf16 v[66:81], v[138:141], v[134:137], v[66:81]
	ds_read_b128 v[134:137], v157 offset:45056
	s_waitcnt lgkmcnt(0)
	v_mfma_f32_32x32x16_bf16 v[66:81], v[134:137], v[130:133], v[66:81]
	ds_read_b128 v[130:133], v159 offset:45056
	s_waitcnt lgkmcnt(0)
	v_mfma_f32_32x32x16_bf16 v[66:81], v[130:133], v[126:129], v[66:81]
	ds_read_b128 v[126:129], v160 offset:45056
	s_waitcnt lgkmcnt(0)
	v_mfma_f32_32x32x16_bf16 v[66:81], v[126:129], v[122:125], v[66:81]
	ds_read_b128 v[122:125], v161 offset:45056
	s_waitcnt lgkmcnt(0)
	v_mfma_f32_32x32x16_bf16 v[66:81], v[122:125], v[118:121], v[66:81]
	ds_read_b128 v[118:121], v162 offset:45056
	v_exp_f32_e32 v122, v97
	s_waitcnt lgkmcnt(0)
	v_mfma_f32_32x32x16_bf16 v[66:81], v[118:121], v[114:117], v[66:81]
	ds_read_b128 v[114:117], v163 offset:45056
	v_exp_f32_e32 v118, v93
	v_exp_f32_e32 v119, v94
	v_exp_f32_e32 v120, v95
	v_exp_f32_e32 v121, v96
	s_waitcnt lgkmcnt(0)
	v_mfma_f32_32x32x16_bf16 v[66:81], v[114:117], v[110:113], v[66:81]
	ds_read_b128 v[110:113], v170 offset:45056
	v_exp_f32_e32 v114, v89
	v_exp_f32_e32 v115, v90
	v_exp_f32_e32 v116, v91
	v_exp_f32_e32 v117, v92
	v_cvt_pk_bf16_f32 v89, v121, v122
	s_waitcnt lgkmcnt(0)
	v_mfma_f32_32x32x16_bf16 v[66:81], v[110:113], v[106:109], v[66:81]
	ds_read_b128 v[106:109], v171 offset:45056
	v_exp_f32_e32 v110, v85
	v_exp_f32_e32 v111, v86
	v_exp_f32_e32 v112, v87
	v_exp_f32_e32 v113, v88
	v_cvt_pk_bf16_f32 v86, v115, v116
	v_cvt_pk_bf16_f32 v87, v117, v118
	s_waitcnt lgkmcnt(0)
	v_mfma_f32_32x32x16_bf16 v[66:81], v[106:109], v[102:105], v[66:81]
	ds_read_b128 v[102:105], v172 offset:45056
	v_exp_f32_e32 v107, v82
	v_exp_f32_e32 v108, v83
	v_exp_f32_e32 v109, v84
	v_cvt_pk_bf16_f32 v84, v111, v112
	v_cvt_pk_bf16_f32 v85, v113, v114
	v_cvt_pk_bf16_f32 v82, v107, v108
	s_waitcnt lgkmcnt(0)
	v_mfma_f32_32x32x16_bf16 v[66:81], v[102:105], v[98:101], v[66:81]
	v_cvt_pk_bf16_f32 v83, v109, v110
	v_cvt_pk_bf16_f32 v88, v119, v120
	v_add_u32_e32 v106, s98, v176
	v_permlane32_swap_b32_e32 v82, v84
	v_permlane32_swap_b32_e32 v83, v85
	v_permlane32_swap_b32_e32 v86, v88
	v_permlane32_swap_b32_e32 v87, v89
	ds_read_b64_tr_b16 v[90:91], v106 offset:0
	ds_read_b64_tr_b16 v[92:93], v106 offset:0x800
	ds_read_b64_tr_b16 v[94:95], v106 offset:0x1000
	ds_read_b64_tr_b16 v[96:97], v106 offset:0x1800
	ds_read_b64_tr_b16 v[98:99], v106 offset:0x200
	ds_read_b64_tr_b16 v[100:101], v106 offset:0xa00
	ds_read_b64_tr_b16 v[102:103], v106 offset:0x1200
	ds_read_b64_tr_b16 v[104:105], v106 offset:0x1a00
	s_waitcnt lgkmcnt(4)
	s_nop 0
	v_mfma_f32_32x32x16_bf16 v[2:17], v[82:85], v[90:93], v[2:17]
	s_nop 2
	v_exp_f32_e32 v123, v66
	v_exp_f32_e32 v124, v67
	v_exp_f32_e32 v125, v68
	v_exp_f32_e32 v126, v69
	v_mfma_f32_32x32x16_bf16 v[2:17], v[86:89], v[94:97], v[2:17]
	ds_read_b64_tr_b16 v[66:67], v106 offset:0x400
	ds_read_b64_tr_b16 v[68:69], v106 offset:0xc00
	ds_read_b64_tr_b16 v[90:91], v106 offset:0x1400
	ds_read_b64_tr_b16 v[92:93], v106 offset:0x1c00
	s_waitcnt lgkmcnt(4)
	v_mfma_f32_32x32x16_bf16 v[18:33], v[82:85], v[98:101], v[18:33]
	v_exp_f32_e32 v98, v70
	v_exp_f32_e32 v99, v71
	v_exp_f32_e32 v100, v72
	v_exp_f32_e32 v101, v73
	v_mfma_f32_32x32x16_bf16 v[18:33], v[86:89], v[102:105], v[18:33]
	ds_read_b64_tr_b16 v[70:71], v106 offset:0x600
	ds_read_b64_tr_b16 v[72:73], v106 offset:0xe00
	ds_read_b64_tr_b16 v[94:95], v106 offset:0x1600
	ds_read_b64_tr_b16 v[96:97], v106 offset:0x1e00
	s_waitcnt lgkmcnt(4)
	v_mfma_f32_32x32x16_bf16 v[34:49], v[82:85], v[66:69], v[34:49]
	v_exp_f32_e32 v102, v74
	v_exp_f32_e32 v103, v75
	v_exp_f32_e32 v104, v76
	v_exp_f32_e32 v105, v77
	v_mfma_f32_32x32x16_bf16 v[34:49], v[86:89], v[90:93], v[34:49]
	ds_read_b64_tr_b16 v[74:75], v106 offset:0x2000
	ds_read_b64_tr_b16 v[76:77], v106 offset:0x2800
	ds_read_b64_tr_b16 v[90:91], v106 offset:0x3000
	ds_read_b64_tr_b16 v[92:93], v106 offset:0x3800
	s_waitcnt lgkmcnt(4)
	v_add_f32_e32 v66, v107, v108
	v_add_f32_e32 v67, v123, v124
	v_mfma_f32_32x32x16_bf16 v[50:65], v[82:85], v[70:73], v[50:65]
	v_add_f32_e32 v66, v66, v109
	v_add_f32_e32 v67, v67, v125
	v_exp_f32_e32 v127, v78
	v_add_f32_e32 v66, v66, v110
	v_add_f32_e32 v67, v67, v126
	v_exp_f32_e32 v128, v79
	v_add_f32_e32 v66, v66, v111
	v_add_f32_e32 v67, v67, v98
	v_mfma_f32_32x32x16_bf16 v[50:65], v[86:89], v[94:97], v[50:65]
	v_add_f32_e32 v66, v66, v112
	v_add_f32_e32 v67, v67, v99
	v_exp_f32_e32 v129, v80
	v_add_f32_e32 v66, v66, v113
	v_add_f32_e32 v67, v67, v100
	v_exp_f32_e32 v81, v81
	v_add_f32_e32 v66, v66, v114
	v_add_f32_e32 v67, v67, v101
	v_cvt_pk_bf16_f32 v68, v123, v124
	v_add_f32_e32 v66, v66, v115
	v_add_f32_e32 v67, v67, v102
	v_cvt_pk_bf16_f32 v69, v125, v126
	v_add_f32_e32 v66, v66, v116
	v_add_f32_e32 v67, v67, v103
	v_cvt_pk_bf16_f32 v70, v98, v99
	v_add_f32_e32 v66, v66, v117
	v_add_f32_e32 v67, v67, v104
	v_cvt_pk_bf16_f32 v71, v100, v101
	v_add_f32_e32 v66, v66, v118
	v_add_f32_e32 v67, v67, v105
	v_cvt_pk_bf16_f32 v78, v102, v103
	v_add_f32_e32 v66, v66, v119
	v_add_f32_e32 v67, v67, v127
	v_cvt_pk_bf16_f32 v79, v104, v105
	v_add_f32_e32 v66, v66, v120
	v_add_f32_e32 v67, v67, v128
	v_cvt_pk_bf16_f32 v80, v127, v128
	v_add_f32_e32 v66, v66, v121
	v_add_f32_e32 v67, v67, v129
	v_permlane32_swap_b32_e32 v68, v70
	v_add_f32_e32 v66, v66, v122
	v_add_f32_e32 v67, v67, v81
	v_cvt_pk_bf16_f32 v81, v129, v81
	v_add_f32_e32 v66, v66, v67
	v_mov_b32_e32 v67, v66
	s_nop 1
	v_permlane32_swap_b32_e32 v66, v67
	v_permlane32_swap_b32_e32 v69, v71
	v_permlane32_swap_b32_e32 v78, v80
	v_permlane32_swap_b32_e32 v79, v81
	ds_read_b64_tr_b16 v[82:83], v106 offset:0x2200
	ds_read_b64_tr_b16 v[84:85], v106 offset:0x2a00
	ds_read_b64_tr_b16 v[86:87], v106 offset:0x3200
	ds_read_b64_tr_b16 v[88:89], v106 offset:0x3a00
	s_waitcnt lgkmcnt(4)
	v_mfma_f32_32x32x16_bf16 v[2:17], v[68:71], v[74:77], v[2:17]
	s_nop 0
	v_mfma_f32_32x32x16_bf16 v[2:17], v[78:81], v[90:93], v[2:17]
	ds_read_b64_tr_b16 v[72:73], v106 offset:0x2400
	ds_read_b64_tr_b16 v[74:75], v106 offset:0x2c00
	ds_read_b64_tr_b16 v[90:91], v106 offset:0x3400
	ds_read_b64_tr_b16 v[92:93], v106 offset:0x3c00
	s_waitcnt lgkmcnt(4)
	v_mfma_f32_32x32x16_bf16 v[18:33], v[68:71], v[82:85], v[18:33]
	v_mfma_f32_32x32x16_bf16 v[18:33], v[78:81], v[86:89], v[18:33]
	ds_read_b64_tr_b16 v[82:83], v106 offset:0x2600
	ds_read_b64_tr_b16 v[84:85], v106 offset:0x2e00
	ds_read_b64_tr_b16 v[86:87], v106 offset:0x3600
	ds_read_b64_tr_b16 v[88:89], v106 offset:0x3e00
	s_waitcnt lgkmcnt(4)
	v_mfma_f32_32x32x16_bf16 v[34:49], v[68:71], v[72:75], v[34:49]
	v_mfma_f32_32x32x16_bf16 v[34:49], v[78:81], v[90:93], v[34:49]
	s_waitcnt lgkmcnt(0)
	v_mfma_f32_32x32x16_bf16 v[50:65], v[68:71], v[82:85], v[50:65]
	s_waitcnt vmcnt(0)
	s_barrier
	v_mfma_f32_32x32x16_bf16 v[50:65], v[78:81], v[86:89], v[50:65]
	s_and_saveexec_b64 s[0:1], s[2:3]
	s_cbranch_execz .LBB0_886
	v_add_f32_e32 v66, v66, v67
	v_lshl_add_u32 v68, v1, 2, s4
	v_add_f32_e32 v66, v151, v66
	ds_write_b32 v68, v66
	s_branch .LBB0_886

	.amdhsa_kernel _Z3fwd4Args
		.amdhsa_group_segment_fixed_size 0
		.amdhsa_private_segment_fixed_size 0
		.amdhsa_kernarg_size 520
		.amdhsa_user_sgpr_count 2
		.amdhsa_user_sgpr_dispatch_ptr 0
		.amdhsa_user_sgpr_queue_ptr 0
		.amdhsa_user_sgpr_kernarg_segment_ptr 1
		.amdhsa_user_sgpr_dispatch_id 0
		.amdhsa_user_sgpr_kernarg_preload_length 0
		.amdhsa_user_sgpr_kernarg_preload_offset 0
		.amdhsa_user_sgpr_private_segment_size 0
		.amdhsa_uses_dynamic_stack 0
		.amdhsa_enable_private_segment 0
		.amdhsa_system_sgpr_workgroup_id_x 1
		.amdhsa_system_sgpr_workgroup_id_y 0
		.amdhsa_system_sgpr_workgroup_id_z 0
		.amdhsa_system_sgpr_workgroup_info 0
		.amdhsa_system_vgpr_workitem_id 0
		.amdhsa_next_free_vgpr 256
		.amdhsa_next_free_sgpr 102
		.amdhsa_accum_offset 256
		.amdhsa_reserve_vcc 1
		.amdhsa_float_round_mode_32 0
		.amdhsa_float_round_mode_16_64 0
		.amdhsa_float_denorm_mode_32 3
		.amdhsa_float_denorm_mode_16_64 3
		.amdhsa_dx10_clamp 1
		.amdhsa_ieee_mode 1
		.amdhsa_fp16_overflow 0
		.amdhsa_tg_split 0
		.amdhsa_exception_fp_ieee_invalid_op 0
		.amdhsa_exception_fp_denorm_src 0
		.amdhsa_exception_fp_ieee_div_zero 0
		.amdhsa_exception_fp_ieee_overflow 0
		.amdhsa_exception_fp_ieee_underflow 0
		.amdhsa_exception_fp_ieee_inexact 0
		.amdhsa_exception_int_div_zero 0
	.end_amdhsa_kernel

amdhsa.kernels:
  - .agpr_count:     0
    .args:
      - .offset:         0
        .size:           264
        .value_kind:     by_value
      - .offset:         264
        .size:           4
        .value_kind:     hidden_block_count_x
      - .offset:         268
        .size:           4
        .value_kind:     hidden_block_count_y
      - .offset:         272
        .size:           4
        .value_kind:     hidden_block_count_z
      - .offset:         276
        .size:           2
        .value_kind:     hidden_group_size_x
      - .offset:         278
        .size:           2
        .value_kind:     hidden_group_size_y
      - .offset:         280
        .size:           2
        .value_kind:     hidden_group_size_z
      - .offset:         282
        .size:           2
        .value_kind:     hidden_remainder_x
      - .offset:         284
        .size:           2
        .value_kind:     hidden_remainder_y
      - .offset:         286
        .size:           2
        .value_kind:     hidden_remainder_z
      - .offset:         304
        .size:           8
        .value_kind:     hidden_global_offset_x
      - .offset:         312
        .size:           8
        .value_kind:     hidden_global_offset_y
      - .offset:         320
        .size:           8
        .value_kind:     hidden_global_offset_z
      - .offset:         328
        .size:           2
        .value_kind:     hidden_grid_dims
      - .offset:         384
        .size:           4
        .value_kind:     hidden_dynamic_lds_size
    .group_segment_fixed_size: 0
    .kernarg_segment_align: 8
    .kernarg_segment_size: 520
    .language:       OpenCL C
    .language_version:
      - 2
      - 0
    .max_flat_workgroup_size: 512
    .name:           _Z3fwd4Args
    .private_segment_fixed_size: 0
    .sgpr_count:     108
    .sgpr_spill_count: 122
    .symbol:         _Z3fwd4Args.kd
    .uniform_work_group_size: 1
    .uses_dynamic_stack: false
    .vgpr_count:     256
    .vgpr_spill_count: 0
    .wavefront_size: 64
